# residual epilogue: x loads pipelined with counted waits, first-half new-residual stores issued before second-half loads are awaited
# speedup vs baseline: 1.0468x; 1.0005x over previous
.LBB0_308:
	v_readlane_b32 s30, v253, 41
	v_readlane_b32 s31, v253, 29
	s_lshl_b32 s38, s30, 1
	s_cmp_eq_u32 s31, 8
	s_cselect_b32 s31, 1, 0
	s_add_i32 s38, s38, s31
	s_ashr_i32 s25, s76, 5
	s_mul_i32 s25, s25, 0x18000
	s_add_u32 s36, s18, s25
	s_addc_u32 s37, s19, 0
	v_lshlrev_b64 v[226:227], 2, v[194:195]
	v_ashrrev_i32_e32 v193, 31, v192
	v_lshlrev_b64 v[228:229], 12, v[192:193]
	v_lshl_add_u64 v[244:245], s[36:37], 0, v[226:227]
	global_load_dwordx4 v[198:201], v[244:245], off offset:0
	global_load_dwordx4 v[202:205], v[244:245], off offset:64
	global_load_dwordx4 v[210:213], v[244:245], off offset:512
	global_load_dwordx4 v[214:217], v[244:245], off offset:576
	v_lshl_add_u64 v[242:243], s[12:13], 0, v[226:227]
	v_lshl_add_u64 v[242:243], v[242:243], 0, v[228:229]
	v_lshl_add_u64 v[248:249], s[10:11], 0, v[226:227]
	v_lshl_add_u64 v[248:249], v[248:249], 0, v[228:229]
	s_mov_b32 s31, 0
	s_mov_b32 s30, 0x0
	v_lshl_add_u64 v[246:247], v[242:243], 0, s[30:31]
	global_load_dwordx4 v[134:137], v[246:247], off offset:0
	global_load_dwordx4 v[138:141], v[246:247], off offset:64
	global_load_dwordx4 v[142:145], v[246:247], off offset:512
	global_load_dwordx4 v[146:149], v[246:247], off offset:576
	s_mov_b32 s30, 0x10000
	v_lshl_add_u64 v[246:247], v[242:243], 0, s[30:31]
	global_load_dwordx4 v[150:153], v[246:247], off offset:0
	global_load_dwordx4 v[154:157], v[246:247], off offset:64
	global_load_dwordx4 v[158:161], v[246:247], off offset:512
	global_load_dwordx4 v[162:165], v[246:247], off offset:576
	s_mov_b32 s30, 0x20000
	v_lshl_add_u64 v[246:247], v[242:243], 0, s[30:31]
	global_load_dwordx4 v[166:169], v[246:247], off offset:0
	global_load_dwordx4 v[170:173], v[246:247], off offset:64
	global_load_dwordx4 v[174:177], v[246:247], off offset:512
	global_load_dwordx4 v[178:181], v[246:247], off offset:576
	s_mov_b32 s30, 0x30000
	v_lshl_add_u64 v[246:247], v[242:243], 0, s[30:31]
	global_load_dwordx4 v[182:185], v[246:247], off offset:0
	global_load_dwordx4 v[186:189], v[246:247], off offset:64
	global_load_dwordx4 v[190:193], v[246:247], off offset:512
	global_load_dwordx4 v[194:197], v[246:247], off offset:576
	s_waitcnt vmcnt(12)
	v_pk_fma_f32 v[130:131], v[130:131], v[198:199], v[134:135]
	v_pk_fma_f32 v[132:133], v[132:133], v[200:201], v[136:137]
	v_pk_fma_f32 v[126:127], v[126:127], v[202:203], v[138:139]
	v_pk_fma_f32 v[128:129], v[128:129], v[204:205], v[140:141]
	v_pk_fma_f32 v[122:123], v[122:123], v[210:211], v[142:143]
	v_pk_fma_f32 v[124:125], v[124:125], v[212:213], v[144:145]
	v_pk_fma_f32 v[118:119], v[118:119], v[214:215], v[146:147]
	v_pk_fma_f32 v[120:121], v[120:121], v[216:217], v[148:149]
	s_mov_b32 s30, 0x80000
	v_lshl_add_u64 v[246:247], v[242:243], 0, s[30:31]
	global_load_dwordx4 v[134:137], v[246:247], off offset:0
	global_load_dwordx4 v[138:141], v[246:247], off offset:64
	global_load_dwordx4 v[142:145], v[246:247], off offset:512
	global_load_dwordx4 v[146:149], v[246:247], off offset:576
	s_waitcnt vmcnt(12)
	v_pk_fma_f32 v[114:115], v[114:115], v[198:199], v[150:151]
	v_pk_fma_f32 v[116:117], v[116:117], v[200:201], v[152:153]
	v_pk_fma_f32 v[110:111], v[110:111], v[202:203], v[154:155]
	v_pk_fma_f32 v[112:113], v[112:113], v[204:205], v[156:157]
	v_pk_fma_f32 v[106:107], v[106:107], v[210:211], v[158:159]
	v_pk_fma_f32 v[108:109], v[108:109], v[212:213], v[160:161]
	v_pk_fma_f32 v[102:103], v[102:103], v[214:215], v[162:163]
	v_pk_fma_f32 v[104:105], v[104:105], v[216:217], v[164:165]
	s_mov_b32 s30, 0x90000
	v_lshl_add_u64 v[246:247], v[242:243], 0, s[30:31]
	global_load_dwordx4 v[150:153], v[246:247], off offset:0
	global_load_dwordx4 v[154:157], v[246:247], off offset:64
	global_load_dwordx4 v[158:161], v[246:247], off offset:512
	global_load_dwordx4 v[162:165], v[246:247], off offset:576
	s_waitcnt vmcnt(12)
	v_pk_fma_f32 v[98:99], v[98:99], v[198:199], v[166:167]
	v_pk_fma_f32 v[100:101], v[100:101], v[200:201], v[168:169]
	v_pk_fma_f32 v[94:95], v[94:95], v[202:203], v[170:171]
	v_pk_fma_f32 v[96:97], v[96:97], v[204:205], v[172:173]
	v_pk_fma_f32 v[90:91], v[90:91], v[210:211], v[174:175]
	v_pk_fma_f32 v[92:93], v[92:93], v[212:213], v[176:177]
	v_pk_fma_f32 v[86:87], v[86:87], v[214:215], v[178:179]
	v_pk_fma_f32 v[88:89], v[88:89], v[216:217], v[180:181]
	s_mov_b32 s30, 0xa0000
	v_lshl_add_u64 v[246:247], v[242:243], 0, s[30:31]
	global_load_dwordx4 v[166:169], v[246:247], off offset:0
	global_load_dwordx4 v[170:173], v[246:247], off offset:64
	global_load_dwordx4 v[174:177], v[246:247], off offset:512
	global_load_dwordx4 v[178:181], v[246:247], off offset:576
	s_waitcnt vmcnt(12)
	v_pk_fma_f32 v[82:83], v[82:83], v[198:199], v[182:183]
	v_pk_fma_f32 v[84:85], v[84:85], v[200:201], v[184:185]
	v_pk_fma_f32 v[78:79], v[78:79], v[202:203], v[186:187]
	v_pk_fma_f32 v[80:81], v[80:81], v[204:205], v[188:189]
	v_pk_fma_f32 v[74:75], v[74:75], v[210:211], v[190:191]
	v_pk_fma_f32 v[76:77], v[76:77], v[212:213], v[192:193]
	v_pk_fma_f32 v[70:71], v[70:71], v[214:215], v[194:195]
	v_pk_fma_f32 v[72:73], v[72:73], v[216:217], v[196:197]
	s_mov_b32 s30, 0xb0000
	v_lshl_add_u64 v[246:247], v[242:243], 0, s[30:31]
	global_load_dwordx4 v[182:185], v[246:247], off offset:0
	global_load_dwordx4 v[186:189], v[246:247], off offset:64
	global_load_dwordx4 v[190:193], v[246:247], off offset:512
	global_load_dwordx4 v[194:197], v[246:247], off offset:576
	s_cmp_eq_u32 s38, 7
	s_cbranch_scc0 .Lrn_st0
	s_waitcnt vmcnt(0)
	s_branch .Lrn_fma1
.Lrn_st0:
	s_mov_b32 s30, 0x0
	v_lshl_add_u64 v[246:247], v[248:249], 0, s[30:31]
	global_store_dwordx4 v[246:247], v[130:133], off offset:0
	global_store_dwordx4 v[246:247], v[126:129], off offset:64
	global_store_dwordx4 v[246:247], v[122:125], off offset:512
	global_store_dwordx4 v[246:247], v[118:121], off offset:576
	s_mov_b32 s30, 0x10000
	v_lshl_add_u64 v[246:247], v[248:249], 0, s[30:31]
	global_store_dwordx4 v[246:247], v[114:117], off offset:0
	global_store_dwordx4 v[246:247], v[110:113], off offset:64
	global_store_dwordx4 v[246:247], v[106:109], off offset:512
	global_store_dwordx4 v[246:247], v[102:105], off offset:576
	s_mov_b32 s30, 0x20000
	v_lshl_add_u64 v[246:247], v[248:249], 0, s[30:31]
	global_store_dwordx4 v[246:247], v[98:101], off offset:0
	global_store_dwordx4 v[246:247], v[94:97], off offset:64
	global_store_dwordx4 v[246:247], v[90:93], off offset:512
	global_store_dwordx4 v[246:247], v[86:89], off offset:576
	s_mov_b32 s30, 0x30000
	v_lshl_add_u64 v[246:247], v[248:249], 0, s[30:31]
	global_store_dwordx4 v[246:247], v[82:85], off offset:0
	global_store_dwordx4 v[246:247], v[78:81], off offset:64
	global_store_dwordx4 v[246:247], v[74:77], off offset:512
	global_store_dwordx4 v[246:247], v[70:73], off offset:576
.Lrn_fma1:
	s_waitcnt vmcnt(28)
	v_pk_fma_f32 v[66:67], v[66:67], v[198:199], v[134:135]
	v_pk_fma_f32 v[68:69], v[68:69], v[200:201], v[136:137]
	v_pk_fma_f32 v[62:63], v[62:63], v[202:203], v[138:139]
	v_pk_fma_f32 v[64:65], v[64:65], v[204:205], v[140:141]
	v_pk_fma_f32 v[58:59], v[58:59], v[210:211], v[142:143]
	v_pk_fma_f32 v[60:61], v[60:61], v[212:213], v[144:145]
	v_pk_fma_f32 v[54:55], v[54:55], v[214:215], v[146:147]
	v_pk_fma_f32 v[56:57], v[56:57], v[216:217], v[148:149]
	s_waitcnt vmcnt(24)
	v_pk_fma_f32 v[50:51], v[50:51], v[198:199], v[150:151]
	v_pk_fma_f32 v[52:53], v[52:53], v[200:201], v[152:153]
	v_pk_fma_f32 v[46:47], v[46:47], v[202:203], v[154:155]
	v_pk_fma_f32 v[48:49], v[48:49], v[204:205], v[156:157]
	v_pk_fma_f32 v[42:43], v[42:43], v[210:211], v[158:159]
	v_pk_fma_f32 v[44:45], v[44:45], v[212:213], v[160:161]
	v_pk_fma_f32 v[38:39], v[38:39], v[214:215], v[162:163]
	v_pk_fma_f32 v[40:41], v[40:41], v[216:217], v[164:165]
	s_waitcnt vmcnt(20)
	v_pk_fma_f32 v[34:35], v[34:35], v[198:199], v[166:167]
	v_pk_fma_f32 v[36:37], v[36:37], v[200:201], v[168:169]
	v_pk_fma_f32 v[30:31], v[30:31], v[202:203], v[170:171]
	v_pk_fma_f32 v[32:33], v[32:33], v[204:205], v[172:173]
	v_pk_fma_f32 v[26:27], v[26:27], v[210:211], v[174:175]
	v_pk_fma_f32 v[28:29], v[28:29], v[212:213], v[176:177]
	v_pk_fma_f32 v[22:23], v[22:23], v[214:215], v[178:179]
	v_pk_fma_f32 v[24:25], v[24:25], v[216:217], v[180:181]
	s_waitcnt vmcnt(16)
	v_pk_fma_f32 v[18:19], v[18:19], v[198:199], v[182:183]
	v_pk_fma_f32 v[20:21], v[20:21], v[200:201], v[184:185]
	v_pk_fma_f32 v[14:15], v[14:15], v[202:203], v[186:187]
	v_pk_fma_f32 v[16:17], v[16:17], v[204:205], v[188:189]
	v_pk_fma_f32 v[10:11], v[10:11], v[210:211], v[190:191]
	v_pk_fma_f32 v[12:13], v[12:13], v[212:213], v[192:193]
	v_pk_fma_f32 v[6:7], v[6:7], v[214:215], v[194:195]
	v_pk_fma_f32 v[8:9], v[8:9], v[216:217], v[196:197]
	s_cmp_eq_u32 s38, 7
	s_cbranch_scc1 .Lrn_final_p
	s_and_b32 s25, s38, 1
	s_lshr_b32 s30, s38, 1
	s_cmp_eq_u32 s25, 0
	s_cbranch_scc1 .Lrn_ffn_p
	s_add_i32 s30, s30, 1
	s_movk_i32 s25, 0x48
	s_mul_i32 s31, s30, 0x6000
	s_branch .Lrn_p_done

.Lrn_xst:
	s_cmp_eq_u32 s38, 7
	s_cbranch_scc1 .Lrn_xst_done
	v_lshl_add_u64 v[242:243], s[10:11], 0, v[226:227]
	v_lshl_add_u64 v[242:243], v[242:243], 0, v[228:229]
	v_add_co_u32_e32 v246, vcc, 0x80000, v242
	v_addc_co_u32_e32 v247, vcc, 0, v243, vcc
	global_store_dwordx4 v[246:247], v[66:69], off offset:0
	global_store_dwordx4 v[246:247], v[62:65], off offset:64
	global_store_dwordx4 v[246:247], v[58:61], off offset:512
	global_store_dwordx4 v[246:247], v[54:57], off offset:576
	v_add_co_u32_e32 v246, vcc, 0x90000, v242
	v_addc_co_u32_e32 v247, vcc, 0, v243, vcc
	global_store_dwordx4 v[246:247], v[50:53], off offset:0
	global_store_dwordx4 v[246:247], v[46:49], off offset:64
	global_store_dwordx4 v[246:247], v[42:45], off offset:512
	global_store_dwordx4 v[246:247], v[38:41], off offset:576
	v_add_co_u32_e32 v246, vcc, 0xa0000, v242
	v_addc_co_u32_e32 v247, vcc, 0, v243, vcc
	global_store_dwordx4 v[246:247], v[34:37], off offset:0
	global_store_dwordx4 v[246:247], v[30:33], off offset:64
	global_store_dwordx4 v[246:247], v[26:29], off offset:512
	global_store_dwordx4 v[246:247], v[22:25], off offset:576
	v_add_co_u32_e32 v246, vcc, 0xb0000, v242
	v_addc_co_u32_e32 v247, vcc, 0, v243, vcc
	global_store_dwordx4 v[246:247], v[18:21], off offset:0
	global_store_dwordx4 v[246:247], v[14:17], off offset:64
	global_store_dwordx4 v[246:247], v[10:13], off offset:512
	global_store_dwordx4 v[246:247], v[6:9], off offset:576
